# strategy 7.4 mirror: one static s_setprio 1 for waves 0..3 (first half) at kernel entry
# speedup vs baseline: 1.0092x; 1.0092x over previous
; #define LAS __attribute__((address_space(3)))
; __global__ void __launch_bounds__(NTHREADS, 2) mk_fwd(Args args) {
;     extern __shared__ __attribute__((aligned(16))) unsigned char lds_raw[];
;     LAS unsigned char* lds = (LAS unsigned char*)lds_raw;
;     const int tid = threadIdx.x, lane = tid & 63, wave = __builtin_amdgcn_readfirstlane(tid >> 6);
.LBB0_5:
	s_or_b64 exec, exec, s[4:5]
	s_lshr_b32 s2, s2, 6
	s_cmp_lt_u32 s2, 4
	s_cbranch_scc0 .Lprio_done
	s_setprio 1
